# P5: odd workgroups run the sample-row skinny tile before their GEMM unit, even ones after (epilogue HBM burst of one half overlaps the other half's skinny tile)
# speedup vs baseline: 1.0182x; 1.0000x over previous
; __global__ void __launch_bounds__(NWAVES * 64, 2) hymba_fwd(Args args) {
;     ...
;     if (IN(5)) {
;         pg8::Gemm g{(const bf16*)(ws + WS_H), (const bf16*)(ws + WS_WD), MP, DM, DFF}; pg8::StaticOrder S; S.init(MP, DM, F.G, (int)blockIdx.x);
;         pg8::EpiDown E{args.out, ws};
;         pg8::gemm_phase<pg8::EpiDown, pg8::StaticOrder, PG8_ALIGN, PG8_SP2>(F.lds + RING_OFF, g, S, E);
;         skinny_tile<DFF, 1>(F, args, (const bf16*)(ws + WS_H), (const bf16*)(ws + WS_WD));
.LBB0_1402:
	s_mov_b32 s94, 0
	s_cmp_lt_i32 s92, 6
	s_cselect_b64 s[0:1], -1, 0
	s_cmp_gt_i32 s93, 5
	s_cselect_b64 s[2:3], -1, 0
	s_and_b64 s[0:1], s[0:1], s[2:3]
	s_andn2_b64 vcc, exec, s[0:1]
	s_cbranch_vccnz .LBB0_1436
.Lp5_setup:
	v_readlane_b32 s0, v251, 4
	v_readlane_b32 s1, v251, 5
	s_add_u32 s4, s0, 0xdc00000
	s_addc_u32 s5, s1, 0
	s_add_u32 s6, s0, 0x1600000
	s_addc_u32 s7, s1, 0
	s_cmpk_lt_i32 s96, 0x100
	s_cselect_b64 s[8:9], -1, 0
	s_cmpk_gt_i32 s96, 0xff
	v_readfirstlane_b32 s2, v0
	s_cbranch_scc1 .LBB0_1431
	s_cmp_lg_u32 s94, 0
	s_cbranch_scc1 .Lp5_go
	s_bitcmp1_b32 s96, 0
	s_cbranch_scc0 .Lp5_go
	s_mov_b32 s94, 1
	v_mov_b32_e32 v250, v0
	s_branch .LBB0_1431
.Lp5_go:
	s_ashr_i32 s33, s96, 31
	s_lshr_b32 s0, s33, 29
	s_add_i32 s11, s96, s0
	s_and_b32 s0, s11, -8
	s_sub_i32 s3, s96, s0
	s_cmp_gt_i32 s3, -1
	s_cbranch_scc0 .LBB0_1406
	s_lshl_b32 s10, s3, 5
	s_ashr_i32 s1, s11, 3
	s_cbranch_execz .LBB0_1407
	s_branch .LBB0_1408

; template <int K, int MODE>
; __device__ __forceinline__ void skinny_tile(Frame& F, const Args& A, const bf16* Am  , const bf16* Bt  ) {
;     int lane = (int)threadIdx.x & 63; asm volatile("" : "+v"(lane));
;     const int w = F.wave, il = lane & 31, hi = lane >> 5;
;     for (int tile = (int)blockIdx.x; tile < 256; tile += (int)gridDim.x) {
;     const int r0 = 64 * (tile >> 5), c0 = 32 * (tile & 31);
;     constexpr int KW = K / 8, NK = KW / 16;
;     const char* ab = (const char*)Am; const char* bb = (const char*)Bt; const int arow = MP + r0 + il, brow = c0 + il, kc0 = w * KW + 8 * hi;
.LBB0_1431:
	s_cmp_eq_u32 s94, 2
	s_cbranch_scc1 .Lp5_end
	s_andn2_b64 vcc, exec, s[8:9]
	s_cbranch_vccnz .LBB0_1436
	v_readlane_b32 s0, v251, 49
	v_readlane_b32 s1, v251, 50
	v_readlane_b32 s3, v251, 0
	v_and_b32_e32 v34, 31, v200
	s_lshr_b32 s1, s3, 8
	s_bfe_u32 s3, s3, 0x20006
	v_ashrrev_i32_e32 v0, 5, v200
	s_mul_i32 s2, s0, 0x160
	s_lshl_b32 s0, s0, 13
	s_lshl_b32 s8, s1, 12
	v_lshl_or_b32 v38, s1, 5, v34
	s_lshl_b32 s1, s3, 3
	v_lshlrev_b32_e32 v1, 2, v200
	v_lshl_add_u32 v39, v0, 2, s1
	s_add_i32 s0, s0, 0
	v_lshl_add_u32 v0, v0, 3, s2
	v_lshrrev_b32_e32 v2, 1, v200
	s_lshl_b32 s9, s3, 10
	v_add_u32_e32 v40, s0, v1
	s_add_i32 s8, s8, 0
	v_readlane_b32 s0, v251, 4
	v_add_u32_e32 v41, 0xa0, v0
	v_lshlrev_b32_e32 v0, 6, v34
	v_and_b32_e32 v35, 16, v1
	v_and_b32_e32 v36, 12, v2
	v_lshlrev_b32_e32 v2, 1, v200
	v_add_u32_e32 v1, s8, v1
	v_readlane_b32 s1, v251, 5
	s_add_u32 s0, s0, 0xba00000
	v_and_b32_e32 v43, 0x3c0, v0
	v_lshlrev_b32_e32 v0, 2, v34
	v_and_b32_e32 v37, 32, v2
	s_addc_u32 s1, s1, 0
	v_mov_b32_e32 v42, 0x3e3
	v_and_b32_e32 v44, 32, v0
	v_mov_b32_e32 v33, 0
	v_add_u32_e32 v45, s9, v1

; __global__ void __launch_bounds__(NWAVES * 64, 2) hymba_fwd(Args args) {
;     ...
;         skinny_tile<DFF, 1>(F, args, (const bf16*)(ws + WS_H), (const bf16*)(ws + WS_WD));
;     }
.LBB0_1436:
	s_cmp_eq_u32 s94, 1
	s_cbranch_scc1 .Lp5_back

; __global__ void __launch_bounds__(NWAVES * 64, 2) hymba_fwd(Args args) {
;     ...
;         pg8::Gemm g{(const bf16*)(ws + WS_H), (const bf16*)(ws + WS_WD), MP, DM, DFF}; pg8::StaticOrder S; S.init(MP, DM, F.G, (int)blockIdx.x);
;         pg8::EpiDown E{args.out, ws};
;         pg8::gemm_phase<pg8::EpiDown, pg8::StaticOrder, PG8_ALIGN, PG8_SP2>(F.lds + RING_OFF, g, S, E);
;         skinny_tile<DFF, 1>(F, args, (const bf16*)(ws + WS_H), (const bf16*)(ws + WS_WD));
.Lp5_back:
	s_mov_b32 s94, 2
	v_readlane_b32 s2, v251, 3
	v_mov_b32_e32 v0, v250
	s_waitcnt vmcnt(0) lgkmcnt(0)
	s_nop 1
	s_sub_i32 s96, s96, s2
	s_barrier
	s_branch .Lp5_setup
